# v21: v19 + the prompt tiles of the branch projections (matrix-bound, independent of the sample attention) now run inside the sample-attention phase, half of the workgroups before and half after their
# speedup vs baseline: 1.0230x; 1.0230x over previous
.LBB0_1679:
	s_cmp_lt_i32 s96, 8
	s_cselect_b64 s[14:15], -1, 0
	s_and_b64 s[0:1], s[14:15], s[0:1]
	s_andn2_b64 vcc, exec, s[0:1]
	s_cbranch_vccnz .LBB0_1962
	s_mov_b32 s0, 0
	v_writelane_b32 v255, s0, 0
	s_bitcmp1_b32 s94, 3
	s_cbranch_scc0 .Lsattn_body
	v_writelane_b32 v255, s14, 1
	v_writelane_b32 v255, s15, 2
	v_writelane_b32 v255, s64, 3
	v_writelane_b32 v255, s65, 4
	v_writelane_b32 v255, s66, 5
	v_writelane_b32 v255, s67, 6
	v_writelane_b32 v255, s68, 7
	v_writelane_b32 v255, s69, 8
	v_writelane_b32 v255, s70, 9
	v_writelane_b32 v255, s71, 10
	v_writelane_b32 v255, s72, 11
	v_writelane_b32 v255, s73, 12
	v_writelane_b32 v255, s74, 13
	v_writelane_b32 v255, s75, 14
	v_writelane_b32 v255, s76, 15
	v_writelane_b32 v255, s77, 16
	v_writelane_b32 v255, s78, 17
	v_writelane_b32 v255, s79, 18
	s_branch .Lbr_body
.Lbr_ret_a:
	v_readlane_b32 s14, v255, 1
	v_readlane_b32 s15, v255, 2
	v_readlane_b32 s64, v255, 3
	v_readlane_b32 s65, v255, 4
	v_readlane_b32 s66, v255, 5
	v_readlane_b32 s67, v255, 6
	v_readlane_b32 s68, v255, 7
	v_readlane_b32 s69, v255, 8
	v_readlane_b32 s70, v255, 9
	v_readlane_b32 s71, v255, 10
	v_readlane_b32 s72, v255, 11
	v_readlane_b32 s73, v255, 12
	v_readlane_b32 s74, v255, 13
	v_readlane_b32 s75, v255, 14
	v_readlane_b32 s76, v255, 15
	v_readlane_b32 s77, v255, 16
	v_readlane_b32 s78, v255, 17
	v_readlane_b32 s79, v255, 18
.Lsattn_body:
	s_add_u32 s20, s90, 0x4ba29600
	s_addc_u32 s21, s91, 0
	s_add_u32 s0, s90, 0x25c2b600
	s_addc_u32 s1, s91, 0
	s_add_u32 s12, s90, 0x1132b600
	s_addc_u32 s13, s91, 0
	s_add_u32 s10, s90, 0x1232b600
	s_mov_b64 s[72:73], s[68:69]
	s_mov_b64 s[68:69], s[64:65]
	v_readlane_b32 s36, v239, 3
	v_readlane_b32 s52, v239, 19
	s_addc_u32 s11, s91, 0
	v_readlane_b32 s46, v239, 13
	v_readlane_b32 s47, v239, 14
	v_readlane_b32 s54, v239, 21
	v_readlane_b32 s55, v239, 22
	v_readlane_b32 s53, v239, 20
	v_readlane_b32 s56, v239, 23
	v_readlane_b32 s57, v239, 24
	v_readlane_b32 s58, v239, 25
	v_readlane_b32 s59, v239, 26
	v_readlane_b32 s60, v239, 27
	v_readlane_b32 s61, v239, 28
	v_readlane_b32 s62, v239, 29
	v_readlane_b32 s63, v239, 30
	v_readlane_b32 s64, v239, 31
	v_readlane_b32 s65, v239, 32
	v_readlane_b32 s66, v239, 33
	v_readlane_b32 s67, v239, 34
	v_readlane_b32 s37, v239, 4
	v_readlane_b32 s38, v239, 5
	v_readlane_b32 s39, v239, 6
	v_readlane_b32 s40, v239, 7
	v_readlane_b32 s41, v239, 8
	v_readlane_b32 s42, v239, 9
	v_readlane_b32 s43, v239, 10
	v_readlane_b32 s44, v239, 11
	v_readlane_b32 s45, v239, 12
	v_readlane_b32 s48, v239, 15
	v_readlane_b32 s49, v239, 16
	v_readlane_b32 s50, v239, 17
	v_readlane_b32 s51, v239, 18
	v_writelane_b32 v239, s52, 19
	s_add_u32 s2, s88, 0x6280000
	s_addc_u32 s3, s89, 0
	v_writelane_b32 v239, s53, 20
	v_writelane_b32 v239, s54, 21
	v_writelane_b32 v239, s55, 22
	v_writelane_b32 v239, s56, 23
	v_writelane_b32 v239, s57, 24
	v_writelane_b32 v239, s58, 25
	v_writelane_b32 v239, s59, 26
	v_writelane_b32 v239, s60, 27
	v_writelane_b32 v239, s61, 28
	v_writelane_b32 v239, s62, 29
	s_add_u32 s16, s90, 0x9d9b600
	v_writelane_b32 v239, s63, 30
	s_addc_u32 s17, s91, 0
	v_writelane_b32 v239, s64, 31
	s_add_u32 s6, s90, 0x44c71600
	v_writelane_b32 v239, s65, 32
	s_addc_u32 s7, s91, 0
	v_writelane_b32 v239, s66, 33
	v_writelane_b32 v239, s67, 34
	v_mbcnt_hi_u32_b32 v147, -1, v216
	v_writelane_b32 v239, s36, 3
	s_and_b32 s8, s87, 0xffffffc0
	v_add_u32_e32 v146, s8, v147
	v_writelane_b32 v239, s37, 4
	v_writelane_b32 v239, s38, 5
	v_writelane_b32 v239, s39, 6
	v_writelane_b32 v239, s40, 7
	v_writelane_b32 v239, s41, 8
	v_writelane_b32 v239, s42, 9
	v_writelane_b32 v239, s43, 10
	v_writelane_b32 v239, s44, 11
	s_mov_b32 s0, 0xfe03f81
	v_writelane_b32 v239, s45, 12
	s_waitcnt vmcnt(0)
	v_mul_hi_i32 v0, v146, s0
	v_writelane_b32 v239, s46, 13
	v_lshrrev_b32_e32 v1, 31, v0
	v_ashrrev_i32_e32 v0, 3, v0
	v_writelane_b32 v239, s47, 14
	v_add_u32_e32 v85, v0, v1
	v_writelane_b32 v239, s48, 15
	v_lshl_add_u32 v0, v85, 7, v85
	v_writelane_b32 v239, s49, 16
	v_sub_u32_e32 v84, v146, v0
	s_mov_b64 s[56:57], s[68:69]
	s_mov_b64 s[60:61], s[72:73]
	s_mov_b64 s[68:69], s[76:77]
	v_writelane_b32 v239, s50, 17
	v_max_i32_e32 v0, 0, v84
	v_cmp_lt_i32_e32 vcc, 15, v84
	v_writelane_b32 v239, s51, 18
	s_and_saveexec_b64 s[4:5], vcc
	s_cbranch_execz .LBB0_1682
	v_cvt_f32_u32_e32 v0, v0
	s_mov_b32 s0, 0x800000
	s_mov_b32 s1, 0x7f800000
	s_mov_b32 s9, 0x40051592
	v_mul_f32_e32 v0, 0x3d800000, v0
	v_cmp_gt_f32_e32 vcc, s0, v0
	s_mov_b32 s0, 0x3f317217
	s_nop 0
	v_cndmask_b32_e64 v1, 0, 32, vcc
	v_ldexp_f32 v0, v0, v1
	v_log_f32_e32 v0, v0
	v_mov_b32_e32 v1, 0x41b17218
	v_cndmask_b32_e32 v1, 0, v1, vcc
	v_mul_f32_e32 v2, 0x3f317217, v0
	v_fma_f32 v2, v0, s0, -v2
	v_fmamk_f32 v2, v0, 0x3377d1cf, v2
	v_fmac_f32_e32 v2, 0x3f317217, v0
	v_cmp_lt_f32_e64 s[0:1], |v0|, s1
	s_nop 1
	v_cndmask_b32_e64 v0, v0, v2, s[0:1]
	v_sub_f32_e32 v0, v0, v1
	v_div_scale_f32 v1, s[0:1], s9, s9, v0
	v_rcp_f32_e32 v2, v1
	s_nop 0
	v_fma_f32 v3, -v1, v2, 1.0
	v_fmac_f32_e32 v2, v3, v2
	v_div_scale_f32 v3, vcc, v0, s9, v0
	v_mul_f32_e32 v4, v3, v2
	v_fma_f32 v5, -v1, v4, v3
	v_fmac_f32_e32 v4, v5, v2
	v_fma_f32 v1, -v1, v4, v3
	v_div_fmas_f32 v1, v1, v2, v4
	v_div_fixup_f32 v0, v1, s9, v0
	v_mul_f32_e32 v0, 0x41800000, v0
	v_cvt_i32_f32_e32 v0, v0
	v_min_i32_e32 v0, 15, v0
	v_add_u32_e32 v0, 16, v0

.LBB0_1961:
	s_or_b64 exec, exec, s[2:3]
	s_waitcnt vmcnt(0) lgkmcnt(0)
	s_barrier
	s_bitcmp1_b32 s94, 3
	s_cbranch_scc1 .LBB0_1962
	v_writelane_b32 v255, s14, 1
	v_writelane_b32 v255, s15, 2
	v_writelane_b32 v255, s64, 3
	v_writelane_b32 v255, s65, 4
	v_writelane_b32 v255, s66, 5
	v_writelane_b32 v255, s67, 6
	v_writelane_b32 v255, s68, 7
	v_writelane_b32 v255, s69, 8
	v_writelane_b32 v255, s70, 9
	v_writelane_b32 v255, s71, 10
	v_writelane_b32 v255, s72, 11
	v_writelane_b32 v255, s73, 12
	v_writelane_b32 v255, s74, 13
	v_writelane_b32 v255, s75, 14
	v_writelane_b32 v255, s76, 15
	v_writelane_b32 v255, s77, 16
	v_writelane_b32 v255, s78, 17
	v_writelane_b32 v255, s79, 18
	s_branch .Lbr_body

.LBB0_2144:
	s_cmp_lt_i32 s96, 10
	s_cselect_b64 s[4:5], -1, 0
	s_and_b64 s[0:1], s[4:5], s[0:1]
	s_andn2_b64 vcc, exec, s[0:1]
	s_mov_b64 s[80:81], s[76:77]
	s_cbranch_vccnz .LBB0_2177
	s_mov_b32 s6, 1
	v_writelane_b32 v255, s6, 0
	s_cmp_gt_i32 s94, 63
	s_cbranch_scc1 .LBB0_2177
.Lbr_body:
	v_readlane_b32 s6, v255, 0
	s_nop 0
	s_lshl_b32 s7, s6, 8
	s_sub_i32 s7, 0x100, s7
	s_add_i32 s7, s7, s94
	s_cmp_lt_i32 s7, 64
	s_cselect_b64 s[0:1], -1, 0
	s_cmp_gt_i32 s7, 63
	s_cbranch_scc0 .LBB0_2150
	s_mov_b64 s[8:9], 0
	s_cmpk_lt_u32 s94, 0x100
	s_mov_b64 s[2:3], 0
	s_cbranch_scc0 .LBB0_2148
	s_lshl_b32 s3, s94, 5
	s_lshr_b32 s2, s94, 3
	s_lshl_b32 s6, s94, 2
	s_and_b32 s3, s3, 32
	s_and_b32 s6, s6, 24
	s_or_b32 s2, s3, s2
	s_bfe_u32 s3, s94, 0x30003
	s_or_b32 s6, s3, s6
	s_lshr_b32 s30, s2, 3
	s_mov_b64 s[2:3], -1

.LBB0_2156:
	s_add_i32 s76, s76, 1
	s_add_i32 s0, s76, s58
	v_readlane_b32 s28, v255, 0
	s_nop 0
	s_lshl_b32 s28, s28, 1
	s_add_i32 s0, s0, s28
	s_cmp_lt_i32 s0, 0
	s_cbranch_scc1 .LBB0_2159
	s_cmp_gt_u32 s0, 1
	s_mov_b64 s[28:29], 0
	s_cbranch_scc1 .LBB0_2160
	s_mov_b32 s75, 16
	s_mov_b32 s2, 0
	s_mov_b64 s[28:29], -1
	s_mov_b32 s18, s62
	s_mov_b32 s20, s63
	s_mov_b32 s77, s0
	s_branch .LBB0_2160

.LBB0_2176:
	s_barrier
	v_readlane_b32 s0, v255, 0
	s_nop 0
	s_cmp_lg_u32 s0, 0
	s_cbranch_scc1 .LBB0_2177
	s_bitcmp1_b32 s94, 3
	s_cbranch_scc1 .Lbr_ret_a
	s_branch .Lbr_ret_b
